# P1 tile order per XCD: 32 concurrent workgroups cover 8 m-tiles x 4 n-tiles of full tiles per round (was 2 x 16); half-width tiles are each owner's ninth tile
# speedup vs baseline: 1.0206x; 1.0192x over previous
;     ...
;   for (int Lx = jx; Lx < (NMT / 8) * NNT; Lx += nbx) {
;     const int grp = Lx / (2 * NNT), gi = Lx % (2 * NNT);
;     const int mt = xcd * (NMT / 8) + 2 * grp + (gi & 1), nt = gi >> 1;
.LBB0_103:
	s_cmp_lt_i32 s58, 0x100
	s_cbranch_scc1 .Lp1_map_full
	s_sub_i32 s6, s58, 0x100
	s_mov_b32 s7, 16
	s_branch .Lp1_map_done
.Lp1_map_full:
	s_lshr_b32 s34, s58, 5
	s_and_b32 s35, s58, 31
	s_and_b32 s6, s35, 7
	s_lshr_b32 s7, s34, 2
	s_lshl_b32 s7, s7, 3
	s_add_i32 s6, s6, s7
	s_lshr_b32 s7, s35, 3
	s_and_b32 s34, s34, 3
	s_lshl_b32 s34, s34, 2
	s_add_i32 s7, s7, s34
.Lp1_map_done:
	s_lshr_b32 s34, s6, 1
	s_and_b32 s35, s6, 1
	s_lshl_b32 s7, s7, 1
	s_or_b32 s35, s35, s7
	s_ashr_i32 s62, s35, 1
	s_cmp_eq_u32 s62, 16
	v_mov_b32_e32 v227, v223
	s_cselect_b64 s[6:7], -1, 0
	s_cmp_lg_u32 s62, 16
	s_mov_b64 s[30:31], -1
	v_readfirstlane_b32 s60, v227
	s_cbranch_scc0 .LBB0_105
	s_bfe_u32 s20, s60, 0x20006
	s_mov_b64 s[30:31], 0
